# PROJ_ODD V^T tiles: DPP quad transposes + cvt_pk, 32 dwordx2 stores per wave instead of 128 short stores; rownorm stores as dwordx4
# speedup vs baseline: 1.0206x; 1.0025x over previous
; DI bf16_t f2bf(float x) { unsigned u = __float_as_uint(x); u += 0x7fffu + ((u >> 16) & 1u); return (bf16_t)(u >> 16); }
; template <int EPI>
; DI void gemm8_epilogue(const GemmArgs& g, f32x4 (&acc)[2][2][4][2], const int brow, const int bcol, const int wr, const int wc, const int fr, const int fq) {
;     ...
;         if (bcol >= 2048) {
;           bf16_t* VT = (bf16_t*)g.out1;
; #pragma unroll
;           for (int m = 0; m < 4; ++m) {
;             const int row = r0 + m * 16, b = row >> 12, t = row & 4095;
; #pragma unroll
;             for (int n = 0; n < 2; ++n)
; #pragma unroll
;               for (int j = 0; j < 4; ++j) {
;                 const int c = cb - 2048 + n * 16 + fq * 4 + j;
;                 VT[((size_t)((b * 16 + (c >> 6)) * 64 + (c & 63))) * SEQ + t] = f2bf(acc[ai][bj][m][n][j]);
;               }
;           }
.LBB0_386:
	v_and_b32_e32 v154, 2, v148
	v_cmp_ne_u32_e64 s[34:35], 0, v154
	v_and_b32_e32 v154, 1, v148
	v_cmp_ne_u32_e64 s[40:41], 0, v154
	v_and_b32_e32 v154, 3, v148
	v_lshrrev_b32_e32 v155, 2, v148
	v_lshlrev_b32_e32 v154, 5, v154
	v_lshl_add_u32 v154, v155, 3, v154
	s_and_b32 s22, s24, 0xfff
	s_lshl_b32 s22, s22, 1
	v_add_u32_e32 v154, s22, v154
	v_mov_b32_e32 v155, 0
	s_ashr_i32 s22, s24, 2
	s_and_b32 s22, s22, 0xfffffc00
	s_add_i32 s22, s22, s23
	v_add_u32_e32 v156, s22, v152
	v_ashrrev_i32_e32 v157, 31, v156
	v_lshlrev_b64 v[156:157], 13, v[156:157]
	v_lshl_add_u64 v[158:159], s[82:83], 0, v[154:155]
	v_lshl_add_u64 v[158:159], v[158:159], 0, v[156:157]
	s_mov_b64 s[50:51], 0x100000
	v_lshl_add_u64 v[160:161], v[158:159], 0, s[50:51]
	s_mov_b64 s[50:51], 0x2000
	s_mov_b64 s[22:23], 0x1a000
	v_cndmask_b32_e64 v154, v110, v126, s[34:35]
	v_cndmask_b32_e64 v155, v102, v118, s[34:35]
	v_cndmask_b32_e64 v156, v46, v62, s[34:35]
	v_cndmask_b32_e64 v157, v38, v54, s[34:35]
	v_mov_b32_dpp v154, v154 quad_perm:[2,3,0,1] row_mask:0xf bank_mask:0xf
	v_mov_b32_dpp v155, v155 quad_perm:[2,3,0,1] row_mask:0xf bank_mask:0xf
	v_mov_b32_dpp v156, v156 quad_perm:[2,3,0,1] row_mask:0xf bank_mask:0xf
	v_mov_b32_dpp v157, v157 quad_perm:[2,3,0,1] row_mask:0xf bank_mask:0xf
	v_cndmask_b32_e64 v126, v126, v154, s[34:35]
	v_cndmask_b32_e64 v110, v154, v110, s[34:35]
	v_cndmask_b32_e64 v118, v118, v155, s[34:35]
	v_cndmask_b32_e64 v102, v155, v102, s[34:35]
	v_cndmask_b32_e64 v62, v62, v156, s[34:35]
	v_cndmask_b32_e64 v46, v156, v46, s[34:35]
	v_cndmask_b32_e64 v54, v54, v157, s[34:35]
	v_cndmask_b32_e64 v38, v157, v38, s[34:35]
	v_cndmask_b32_e64 v154, v118, v126, s[40:41]
	v_cndmask_b32_e64 v155, v102, v110, s[40:41]
	v_cndmask_b32_e64 v156, v54, v62, s[40:41]
	v_cndmask_b32_e64 v157, v38, v46, s[40:41]
	v_mov_b32_dpp v154, v154 quad_perm:[1,0,3,2] row_mask:0xf bank_mask:0xf
	v_mov_b32_dpp v155, v155 quad_perm:[1,0,3,2] row_mask:0xf bank_mask:0xf
	v_mov_b32_dpp v156, v156 quad_perm:[1,0,3,2] row_mask:0xf bank_mask:0xf
	v_mov_b32_dpp v157, v157 quad_perm:[1,0,3,2] row_mask:0xf bank_mask:0xf
	v_cndmask_b32_e64 v126, v126, v154, s[40:41]
	v_cndmask_b32_e64 v118, v154, v118, s[40:41]
	v_cndmask_b32_e64 v110, v110, v155, s[40:41]
	v_cndmask_b32_e64 v102, v155, v102, s[40:41]
	v_cndmask_b32_e64 v62, v62, v156, s[40:41]
	v_cndmask_b32_e64 v54, v156, v54, s[40:41]
	v_cndmask_b32_e64 v46, v46, v157, s[40:41]
	v_cndmask_b32_e64 v38, v157, v38, s[40:41]
	v_cvt_pk_bf16_f32 v164, v126, v118
	v_cvt_pk_bf16_f32 v165, v110, v102
	v_cvt_pk_bf16_f32 v168, v62, v54
	v_cvt_pk_bf16_f32 v169, v46, v38
	global_store_dwordx2 v[158:159], v[164:165], off
	global_store_dwordx2 v[158:159], v[168:169], off offset:256
	v_lshl_add_u64 v[158:159], v[158:159], 0, s[50:51]
	v_cndmask_b32_e64 v154, v111, v127, s[34:35]
	v_cndmask_b32_e64 v155, v103, v119, s[34:35]
	v_cndmask_b32_e64 v156, v47, v63, s[34:35]
	v_cndmask_b32_e64 v157, v39, v55, s[34:35]
	v_mov_b32_dpp v154, v154 quad_perm:[2,3,0,1] row_mask:0xf bank_mask:0xf
	v_mov_b32_dpp v155, v155 quad_perm:[2,3,0,1] row_mask:0xf bank_mask:0xf
	v_mov_b32_dpp v156, v156 quad_perm:[2,3,0,1] row_mask:0xf bank_mask:0xf
	v_mov_b32_dpp v157, v157 quad_perm:[2,3,0,1] row_mask:0xf bank_mask:0xf
	v_cndmask_b32_e64 v127, v127, v154, s[34:35]
	v_cndmask_b32_e64 v111, v154, v111, s[34:35]
	v_cndmask_b32_e64 v119, v119, v155, s[34:35]
	v_cndmask_b32_e64 v103, v155, v103, s[34:35]
	v_cndmask_b32_e64 v63, v63, v156, s[34:35]
	v_cndmask_b32_e64 v47, v156, v47, s[34:35]
	v_cndmask_b32_e64 v55, v55, v157, s[34:35]
	v_cndmask_b32_e64 v39, v157, v39, s[34:35]
	v_cndmask_b32_e64 v154, v119, v127, s[40:41]
	v_cndmask_b32_e64 v155, v103, v111, s[40:41]
	v_cndmask_b32_e64 v156, v55, v63, s[40:41]
	v_cndmask_b32_e64 v157, v39, v47, s[40:41]
	v_mov_b32_dpp v154, v154 quad_perm:[1,0,3,2] row_mask:0xf bank_mask:0xf
	v_mov_b32_dpp v155, v155 quad_perm:[1,0,3,2] row_mask:0xf bank_mask:0xf
	v_mov_b32_dpp v156, v156 quad_perm:[1,0,3,2] row_mask:0xf bank_mask:0xf
	v_mov_b32_dpp v157, v157 quad_perm:[1,0,3,2] row_mask:0xf bank_mask:0xf
	v_cndmask_b32_e64 v127, v127, v154, s[40:41]
	v_cndmask_b32_e64 v119, v154, v119, s[40:41]
	v_cndmask_b32_e64 v111, v111, v155, s[40:41]
	v_cndmask_b32_e64 v103, v155, v103, s[40:41]
	v_cndmask_b32_e64 v63, v63, v156, s[40:41]
	v_cndmask_b32_e64 v55, v156, v55, s[40:41]
	v_cndmask_b32_e64 v47, v47, v157, s[40:41]
	v_cndmask_b32_e64 v39, v157, v39, s[40:41]
	v_cvt_pk_bf16_f32 v164, v127, v119
	v_cvt_pk_bf16_f32 v165, v111, v103
	v_cvt_pk_bf16_f32 v168, v63, v55
	v_cvt_pk_bf16_f32 v169, v47, v39
	global_store_dwordx2 v[158:159], v[164:165], off
	global_store_dwordx2 v[158:159], v[168:169], off offset:256
	v_lshl_add_u64 v[158:159], v[158:159], 0, s[50:51]
	v_cndmask_b32_e64 v154, v112, v128, s[34:35]
	v_cndmask_b32_e64 v155, v104, v120, s[34:35]
	v_cndmask_b32_e64 v156, v48, v64, s[34:35]
	v_cndmask_b32_e64 v157, v40, v56, s[34:35]
	v_mov_b32_dpp v154, v154 quad_perm:[2,3,0,1] row_mask:0xf bank_mask:0xf
	v_mov_b32_dpp v155, v155 quad_perm:[2,3,0,1] row_mask:0xf bank_mask:0xf
	v_mov_b32_dpp v156, v156 quad_perm:[2,3,0,1] row_mask:0xf bank_mask:0xf
	v_mov_b32_dpp v157, v157 quad_perm:[2,3,0,1] row_mask:0xf bank_mask:0xf
	v_cndmask_b32_e64 v128, v128, v154, s[34:35]
	v_cndmask_b32_e64 v112, v154, v112, s[34:35]
	v_cndmask_b32_e64 v120, v120, v155, s[34:35]
	v_cndmask_b32_e64 v104, v155, v104, s[34:35]
	v_cndmask_b32_e64 v64, v64, v156, s[34:35]
	v_cndmask_b32_e64 v48, v156, v48, s[34:35]
	v_cndmask_b32_e64 v56, v56, v157, s[34:35]
	v_cndmask_b32_e64 v40, v157, v40, s[34:35]
	v_cndmask_b32_e64 v154, v120, v128, s[40:41]
; DI bf16_t f2bf(float x) { unsigned u = __float_as_uint(x); u += 0x7fffu + ((u >> 16) & 1u); return (bf16_t)(u >> 16); }
; template <int EPI>
; DI void gemm8_epilogue(const GemmArgs& g, f32x4 (&acc)[2][2][4][2], const int brow, const int bcol, const int wr, const int wc, const int fr, const int fq) {
;     ...
;         if (bcol >= 2048) {
;           bf16_t* VT = (bf16_t*)g.out1;
; #pragma unroll
;           for (int m = 0; m < 4; ++m) {
;             const int row = r0 + m * 16, b = row >> 12, t = row & 4095;
; #pragma unroll
;             for (int n = 0; n < 2; ++n)
; #pragma unroll
;               for (int j = 0; j < 4; ++j) {
;                 const int c = cb - 2048 + n * 16 + fq * 4 + j;
;                 VT[((size_t)((b * 16 + (c >> 6)) * 64 + (c & 63))) * SEQ + t] = f2bf(acc[ai][bj][m][n][j]);
;               }
;           }
	v_cndmask_b32_e64 v155, v104, v112, s[40:41]
	v_cndmask_b32_e64 v156, v56, v64, s[40:41]
	v_cndmask_b32_e64 v157, v40, v48, s[40:41]
	v_mov_b32_dpp v154, v154 quad_perm:[1,0,3,2] row_mask:0xf bank_mask:0xf
	v_mov_b32_dpp v155, v155 quad_perm:[1,0,3,2] row_mask:0xf bank_mask:0xf
	v_mov_b32_dpp v156, v156 quad_perm:[1,0,3,2] row_mask:0xf bank_mask:0xf
	v_mov_b32_dpp v157, v157 quad_perm:[1,0,3,2] row_mask:0xf bank_mask:0xf
	v_cndmask_b32_e64 v128, v128, v154, s[40:41]
	v_cndmask_b32_e64 v120, v154, v120, s[40:41]
	v_cndmask_b32_e64 v112, v112, v155, s[40:41]
	v_cndmask_b32_e64 v104, v155, v104, s[40:41]
	v_cndmask_b32_e64 v64, v64, v156, s[40:41]
	v_cndmask_b32_e64 v56, v156, v56, s[40:41]
	v_cndmask_b32_e64 v48, v48, v157, s[40:41]
	v_cndmask_b32_e64 v40, v157, v40, s[40:41]
	v_cvt_pk_bf16_f32 v164, v128, v120
	v_cvt_pk_bf16_f32 v165, v112, v104
	v_cvt_pk_bf16_f32 v168, v64, v56
	v_cvt_pk_bf16_f32 v169, v48, v40
	global_store_dwordx2 v[158:159], v[164:165], off
	global_store_dwordx2 v[158:159], v[168:169], off offset:256
	v_lshl_add_u64 v[158:159], v[158:159], 0, s[50:51]
	v_cndmask_b32_e64 v154, v113, v129, s[34:35]
	v_cndmask_b32_e64 v155, v105, v121, s[34:35]
	v_cndmask_b32_e64 v156, v49, v65, s[34:35]
	v_cndmask_b32_e64 v157, v41, v57, s[34:35]
	v_mov_b32_dpp v154, v154 quad_perm:[2,3,0,1] row_mask:0xf bank_mask:0xf
	v_mov_b32_dpp v155, v155 quad_perm:[2,3,0,1] row_mask:0xf bank_mask:0xf
	v_mov_b32_dpp v156, v156 quad_perm:[2,3,0,1] row_mask:0xf bank_mask:0xf
	v_mov_b32_dpp v157, v157 quad_perm:[2,3,0,1] row_mask:0xf bank_mask:0xf
	v_cndmask_b32_e64 v129, v129, v154, s[34:35]
	v_cndmask_b32_e64 v113, v154, v113, s[34:35]
	v_cndmask_b32_e64 v121, v121, v155, s[34:35]
	v_cndmask_b32_e64 v105, v155, v105, s[34:35]
	v_cndmask_b32_e64 v65, v65, v156, s[34:35]
	v_cndmask_b32_e64 v49, v156, v49, s[34:35]
	v_cndmask_b32_e64 v57, v57, v157, s[34:35]
	v_cndmask_b32_e64 v41, v157, v41, s[34:35]
	v_cndmask_b32_e64 v154, v121, v129, s[40:41]
	v_cndmask_b32_e64 v155, v105, v113, s[40:41]
	v_cndmask_b32_e64 v156, v57, v65, s[40:41]
	v_cndmask_b32_e64 v157, v41, v49, s[40:41]
	v_mov_b32_dpp v154, v154 quad_perm:[1,0,3,2] row_mask:0xf bank_mask:0xf
	v_mov_b32_dpp v155, v155 quad_perm:[1,0,3,2] row_mask:0xf bank_mask:0xf
	v_mov_b32_dpp v156, v156 quad_perm:[1,0,3,2] row_mask:0xf bank_mask:0xf
	v_mov_b32_dpp v157, v157 quad_perm:[1,0,3,2] row_mask:0xf bank_mask:0xf
	v_cndmask_b32_e64 v129, v129, v154, s[40:41]
	v_cndmask_b32_e64 v121, v154, v121, s[40:41]
	v_cndmask_b32_e64 v113, v113, v155, s[40:41]
	v_cndmask_b32_e64 v105, v155, v105, s[40:41]
	v_cndmask_b32_e64 v65, v65, v156, s[40:41]
	v_cndmask_b32_e64 v57, v156, v57, s[40:41]
	v_cndmask_b32_e64 v49, v49, v157, s[40:41]
	v_cndmask_b32_e64 v41, v157, v41, s[40:41]
	v_cvt_pk_bf16_f32 v164, v129, v121
	v_cvt_pk_bf16_f32 v165, v113, v105
	v_cvt_pk_bf16_f32 v168, v65, v57
	v_cvt_pk_bf16_f32 v169, v49, v41
	global_store_dwordx2 v[158:159], v[164:165], off
	global_store_dwordx2 v[158:159], v[168:169], off offset:256
	v_lshl_add_u64 v[158:159], v[158:159], 0, s[22:23]
	v_cndmask_b32_e64 v154, v106, v122, s[34:35]
	v_cndmask_b32_e64 v155, v98, v114, s[34:35]
	v_cndmask_b32_e64 v156, v42, v58, s[34:35]
	v_cndmask_b32_e64 v157, v34, v50, s[34:35]
	v_mov_b32_dpp v154, v154 quad_perm:[2,3,0,1] row_mask:0xf bank_mask:0xf
	v_mov_b32_dpp v155, v155 quad_perm:[2,3,0,1] row_mask:0xf bank_mask:0xf
	v_mov_b32_dpp v156, v156 quad_perm:[2,3,0,1] row_mask:0xf bank_mask:0xf
	v_mov_b32_dpp v157, v157 quad_perm:[2,3,0,1] row_mask:0xf bank_mask:0xf
	v_cndmask_b32_e64 v122, v122, v154, s[34:35]
	v_cndmask_b32_e64 v106, v154, v106, s[34:35]
	v_cndmask_b32_e64 v114, v114, v155, s[34:35]
	v_cndmask_b32_e64 v98, v155, v98, s[34:35]
	v_cndmask_b32_e64 v58, v58, v156, s[34:35]
	v_cndmask_b32_e64 v42, v156, v42, s[34:35]
	v_cndmask_b32_e64 v50, v50, v157, s[34:35]
	v_cndmask_b32_e64 v34, v157, v34, s[34:35]
	v_cndmask_b32_e64 v154, v114, v122, s[40:41]
	v_cndmask_b32_e64 v155, v98, v106, s[40:41]
	v_cndmask_b32_e64 v156, v50, v58, s[40:41]
	v_cndmask_b32_e64 v157, v34, v42, s[40:41]
	v_mov_b32_dpp v154, v154 quad_perm:[1,0,3,2] row_mask:0xf bank_mask:0xf
	v_mov_b32_dpp v155, v155 quad_perm:[1,0,3,2] row_mask:0xf bank_mask:0xf
	v_mov_b32_dpp v156, v156 quad_perm:[1,0,3,2] row_mask:0xf bank_mask:0xf
	v_mov_b32_dpp v157, v157 quad_perm:[1,0,3,2] row_mask:0xf bank_mask:0xf
	v_cndmask_b32_e64 v122, v122, v154, s[40:41]
	v_cndmask_b32_e64 v114, v154, v114, s[40:41]
	v_cndmask_b32_e64 v106, v106, v155, s[40:41]
	v_cndmask_b32_e64 v98, v155, v98, s[40:41]
	v_cndmask_b32_e64 v58, v58, v156, s[40:41]
	v_cndmask_b32_e64 v50, v156, v50, s[40:41]
	v_cndmask_b32_e64 v42, v42, v157, s[40:41]
	v_cndmask_b32_e64 v34, v157, v34, s[40:41]
	v_cvt_pk_bf16_f32 v164, v122, v114
	v_cvt_pk_bf16_f32 v165, v106, v98
	v_cvt_pk_bf16_f32 v168, v58, v50
	v_cvt_pk_bf16_f32 v169, v42, v34
	global_store_dwordx2 v[158:159], v[164:165], off
	global_store_dwordx2 v[158:159], v[168:169], off offset:256
	v_lshl_add_u64 v[158:159], v[158:159], 0, s[50:51]
	v_cndmask_b32_e64 v154, v107, v123, s[34:35]
	v_cndmask_b32_e64 v155, v99, v115, s[34:35]
	v_cndmask_b32_e64 v156, v43, v59, s[34:35]
	v_cndmask_b32_e64 v157, v35, v51, s[34:35]
	v_mov_b32_dpp v154, v154 quad_perm:[2,3,0,1] row_mask:0xf bank_mask:0xf
	v_mov_b32_dpp v155, v155 quad_perm:[2,3,0,1] row_mask:0xf bank_mask:0xf
	v_mov_b32_dpp v156, v156 quad_perm:[2,3,0,1] row_mask:0xf bank_mask:0xf
	v_mov_b32_dpp v157, v157 quad_perm:[2,3,0,1] row_mask:0xf bank_mask:0xf
	v_cndmask_b32_e64 v123, v123, v154, s[34:35]
	v_cndmask_b32_e64 v107, v154, v107, s[34:35]
	v_cndmask_b32_e64 v115, v115, v155, s[34:35]
; DI bf16_t f2bf(float x) { unsigned u = __float_as_uint(x); u += 0x7fffu + ((u >> 16) & 1u); return (bf16_t)(u >> 16); }
; template <int EPI>
; DI void gemm8_epilogue(const GemmArgs& g, f32x4 (&acc)[2][2][4][2], const int brow, const int bcol, const int wr, const int wc, const int fr, const int fq) {
;     ...
;         if (bcol >= 2048) {
;           bf16_t* VT = (bf16_t*)g.out1;
; #pragma unroll
;           for (int m = 0; m < 4; ++m) {
;             const int row = r0 + m * 16, b = row >> 12, t = row & 4095;
; #pragma unroll
;             for (int n = 0; n < 2; ++n)
; #pragma unroll
;               for (int j = 0; j < 4; ++j) {
;                 const int c = cb - 2048 + n * 16 + fq * 4 + j;
;                 VT[((size_t)((b * 16 + (c >> 6)) * 64 + (c & 63))) * SEQ + t] = f2bf(acc[ai][bj][m][n][j]);
;               }
;           }
	v_cndmask_b32_e64 v99, v155, v99, s[34:35]
	v_cndmask_b32_e64 v59, v59, v156, s[34:35]
	v_cndmask_b32_e64 v43, v156, v43, s[34:35]
	v_cndmask_b32_e64 v51, v51, v157, s[34:35]
	v_cndmask_b32_e64 v35, v157, v35, s[34:35]
	v_cndmask_b32_e64 v154, v115, v123, s[40:41]
	v_cndmask_b32_e64 v155, v99, v107, s[40:41]
	v_cndmask_b32_e64 v156, v51, v59, s[40:41]
	v_cndmask_b32_e64 v157, v35, v43, s[40:41]
	v_mov_b32_dpp v154, v154 quad_perm:[1,0,3,2] row_mask:0xf bank_mask:0xf
	v_mov_b32_dpp v155, v155 quad_perm:[1,0,3,2] row_mask:0xf bank_mask:0xf
	v_mov_b32_dpp v156, v156 quad_perm:[1,0,3,2] row_mask:0xf bank_mask:0xf
	v_mov_b32_dpp v157, v157 quad_perm:[1,0,3,2] row_mask:0xf bank_mask:0xf
	v_cndmask_b32_e64 v123, v123, v154, s[40:41]
	v_cndmask_b32_e64 v115, v154, v115, s[40:41]
	v_cndmask_b32_e64 v107, v107, v155, s[40:41]
	v_cndmask_b32_e64 v99, v155, v99, s[40:41]
	v_cndmask_b32_e64 v59, v59, v156, s[40:41]
	v_cndmask_b32_e64 v51, v156, v51, s[40:41]
	v_cndmask_b32_e64 v43, v43, v157, s[40:41]
	v_cndmask_b32_e64 v35, v157, v35, s[40:41]
	v_cvt_pk_bf16_f32 v164, v123, v115
	v_cvt_pk_bf16_f32 v165, v107, v99
	v_cvt_pk_bf16_f32 v168, v59, v51
	v_cvt_pk_bf16_f32 v169, v43, v35
	global_store_dwordx2 v[158:159], v[164:165], off
	global_store_dwordx2 v[158:159], v[168:169], off offset:256
	v_lshl_add_u64 v[158:159], v[158:159], 0, s[50:51]
	v_cndmask_b32_e64 v154, v108, v124, s[34:35]
	v_cndmask_b32_e64 v155, v100, v116, s[34:35]
	v_cndmask_b32_e64 v156, v44, v60, s[34:35]
	v_cndmask_b32_e64 v157, v36, v52, s[34:35]
	v_mov_b32_dpp v154, v154 quad_perm:[2,3,0,1] row_mask:0xf bank_mask:0xf
	v_mov_b32_dpp v155, v155 quad_perm:[2,3,0,1] row_mask:0xf bank_mask:0xf
	v_mov_b32_dpp v156, v156 quad_perm:[2,3,0,1] row_mask:0xf bank_mask:0xf
	v_mov_b32_dpp v157, v157 quad_perm:[2,3,0,1] row_mask:0xf bank_mask:0xf
	v_cndmask_b32_e64 v124, v124, v154, s[34:35]
	v_cndmask_b32_e64 v108, v154, v108, s[34:35]
	v_cndmask_b32_e64 v116, v116, v155, s[34:35]
	v_cndmask_b32_e64 v100, v155, v100, s[34:35]
	v_cndmask_b32_e64 v60, v60, v156, s[34:35]
	v_cndmask_b32_e64 v44, v156, v44, s[34:35]
	v_cndmask_b32_e64 v52, v52, v157, s[34:35]
	v_cndmask_b32_e64 v36, v157, v36, s[34:35]
	v_cndmask_b32_e64 v154, v116, v124, s[40:41]
	v_cndmask_b32_e64 v155, v100, v108, s[40:41]
	v_cndmask_b32_e64 v156, v52, v60, s[40:41]
	v_cndmask_b32_e64 v157, v36, v44, s[40:41]
	v_mov_b32_dpp v154, v154 quad_perm:[1,0,3,2] row_mask:0xf bank_mask:0xf
	v_mov_b32_dpp v155, v155 quad_perm:[1,0,3,2] row_mask:0xf bank_mask:0xf
	v_mov_b32_dpp v156, v156 quad_perm:[1,0,3,2] row_mask:0xf bank_mask:0xf
	v_mov_b32_dpp v157, v157 quad_perm:[1,0,3,2] row_mask:0xf bank_mask:0xf
	v_cndmask_b32_e64 v124, v124, v154, s[40:41]
	v_cndmask_b32_e64 v116, v154, v116, s[40:41]
	v_cndmask_b32_e64 v108, v108, v155, s[40:41]
	v_cndmask_b32_e64 v100, v155, v100, s[40:41]
	v_cndmask_b32_e64 v60, v60, v156, s[40:41]
	v_cndmask_b32_e64 v52, v156, v52, s[40:41]
	v_cndmask_b32_e64 v44, v44, v157, s[40:41]
	v_cndmask_b32_e64 v36, v157, v36, s[40:41]
	v_cvt_pk_bf16_f32 v164, v124, v116
	v_cvt_pk_bf16_f32 v165, v108, v100
	v_cvt_pk_bf16_f32 v168, v60, v52
	v_cvt_pk_bf16_f32 v169, v44, v36
	global_store_dwordx2 v[158:159], v[164:165], off
	global_store_dwordx2 v[158:159], v[168:169], off offset:256
	v_lshl_add_u64 v[158:159], v[158:159], 0, s[50:51]
	v_cndmask_b32_e64 v154, v109, v125, s[34:35]
	v_cndmask_b32_e64 v155, v101, v117, s[34:35]
	v_cndmask_b32_e64 v156, v45, v61, s[34:35]
	v_cndmask_b32_e64 v157, v37, v53, s[34:35]
	v_mov_b32_dpp v154, v154 quad_perm:[2,3,0,1] row_mask:0xf bank_mask:0xf
	v_mov_b32_dpp v155, v155 quad_perm:[2,3,0,1] row_mask:0xf bank_mask:0xf
	v_mov_b32_dpp v156, v156 quad_perm:[2,3,0,1] row_mask:0xf bank_mask:0xf
	v_mov_b32_dpp v157, v157 quad_perm:[2,3,0,1] row_mask:0xf bank_mask:0xf
	v_cndmask_b32_e64 v125, v125, v154, s[34:35]
	v_cndmask_b32_e64 v109, v154, v109, s[34:35]
	v_cndmask_b32_e64 v117, v117, v155, s[34:35]
	v_cndmask_b32_e64 v101, v155, v101, s[34:35]
	v_cndmask_b32_e64 v61, v61, v156, s[34:35]
	v_cndmask_b32_e64 v45, v156, v45, s[34:35]
	v_cndmask_b32_e64 v53, v53, v157, s[34:35]
	v_cndmask_b32_e64 v37, v157, v37, s[34:35]
	v_cndmask_b32_e64 v154, v117, v125, s[40:41]
	v_cndmask_b32_e64 v155, v101, v109, s[40:41]
	v_cndmask_b32_e64 v156, v53, v61, s[40:41]
	v_cndmask_b32_e64 v157, v37, v45, s[40:41]
	v_mov_b32_dpp v154, v154 quad_perm:[1,0,3,2] row_mask:0xf bank_mask:0xf
	v_mov_b32_dpp v155, v155 quad_perm:[1,0,3,2] row_mask:0xf bank_mask:0xf
	v_mov_b32_dpp v156, v156 quad_perm:[1,0,3,2] row_mask:0xf bank_mask:0xf
	v_mov_b32_dpp v157, v157 quad_perm:[1,0,3,2] row_mask:0xf bank_mask:0xf
	v_cndmask_b32_e64 v125, v125, v154, s[40:41]
	v_cndmask_b32_e64 v117, v154, v117, s[40:41]
	v_cndmask_b32_e64 v109, v109, v155, s[40:41]
	v_cndmask_b32_e64 v101, v155, v101, s[40:41]
	v_cndmask_b32_e64 v61, v61, v156, s[40:41]
	v_cndmask_b32_e64 v53, v156, v53, s[40:41]
	v_cndmask_b32_e64 v45, v45, v157, s[40:41]
	v_cndmask_b32_e64 v37, v157, v37, s[40:41]
	v_cvt_pk_bf16_f32 v164, v125, v117
	v_cvt_pk_bf16_f32 v165, v109, v101
	v_cvt_pk_bf16_f32 v168, v61, v53
	v_cvt_pk_bf16_f32 v169, v45, v37
	global_store_dwordx2 v[158:159], v[164:165], off
	global_store_dwordx2 v[158:159], v[168:169], off offset:256
	v_cndmask_b32_e64 v154, v78, v94, s[34:35]
	v_cndmask_b32_e64 v155, v70, v86, s[34:35]
	v_cndmask_b32_e64 v156, v14, v30, s[34:35]
	v_cndmask_b32_e64 v157, v6, v22, s[34:35]
	v_mov_b32_dpp v154, v154 quad_perm:[2,3,0,1] row_mask:0xf bank_mask:0xf
	v_mov_b32_dpp v155, v155 quad_perm:[2,3,0,1] row_mask:0xf bank_mask:0xf
	v_mov_b32_dpp v156, v156 quad_perm:[2,3,0,1] row_mask:0xf bank_mask:0xf
; DI bf16_t f2bf(float x) { unsigned u = __float_as_uint(x); u += 0x7fffu + ((u >> 16) & 1u); return (bf16_t)(u >> 16); }
; template <int EPI>
; DI void gemm8_epilogue(const GemmArgs& g, f32x4 (&acc)[2][2][4][2], const int brow, const int bcol, const int wr, const int wc, const int fr, const int fq) {
;     ...
;         if (bcol >= 2048) {
;           bf16_t* VT = (bf16_t*)g.out1;
; #pragma unroll
;           for (int m = 0; m < 4; ++m) {
;             const int row = r0 + m * 16, b = row >> 12, t = row & 4095;
; #pragma unroll
;             for (int n = 0; n < 2; ++n)
; #pragma unroll
;               for (int j = 0; j < 4; ++j) {
;                 const int c = cb - 2048 + n * 16 + fq * 4 + j;
;                 VT[((size_t)((b * 16 + (c >> 6)) * 64 + (c & 63))) * SEQ + t] = f2bf(acc[ai][bj][m][n][j]);
;               }
;           }
	v_mov_b32_dpp v157, v157 quad_perm:[2,3,0,1] row_mask:0xf bank_mask:0xf
	v_cndmask_b32_e64 v94, v94, v154, s[34:35]
	v_cndmask_b32_e64 v78, v154, v78, s[34:35]
	v_cndmask_b32_e64 v86, v86, v155, s[34:35]
	v_cndmask_b32_e64 v70, v155, v70, s[34:35]
	v_cndmask_b32_e64 v30, v30, v156, s[34:35]
	v_cndmask_b32_e64 v14, v156, v14, s[34:35]
	v_cndmask_b32_e64 v22, v22, v157, s[34:35]
	v_cndmask_b32_e64 v6, v157, v6, s[34:35]
	v_cndmask_b32_e64 v154, v86, v94, s[40:41]
	v_cndmask_b32_e64 v155, v70, v78, s[40:41]
	v_cndmask_b32_e64 v156, v22, v30, s[40:41]
	v_cndmask_b32_e64 v157, v6, v14, s[40:41]
	v_mov_b32_dpp v154, v154 quad_perm:[1,0,3,2] row_mask:0xf bank_mask:0xf
	v_mov_b32_dpp v155, v155 quad_perm:[1,0,3,2] row_mask:0xf bank_mask:0xf
	v_mov_b32_dpp v156, v156 quad_perm:[1,0,3,2] row_mask:0xf bank_mask:0xf
	v_mov_b32_dpp v157, v157 quad_perm:[1,0,3,2] row_mask:0xf bank_mask:0xf
	v_cndmask_b32_e64 v94, v94, v154, s[40:41]
	v_cndmask_b32_e64 v86, v154, v86, s[40:41]
	v_cndmask_b32_e64 v78, v78, v155, s[40:41]
	v_cndmask_b32_e64 v70, v155, v70, s[40:41]
	v_cndmask_b32_e64 v30, v30, v156, s[40:41]
	v_cndmask_b32_e64 v22, v156, v22, s[40:41]
	v_cndmask_b32_e64 v14, v14, v157, s[40:41]
	v_cndmask_b32_e64 v6, v157, v6, s[40:41]
	v_cvt_pk_bf16_f32 v164, v94, v86
	v_cvt_pk_bf16_f32 v165, v78, v70
	v_cvt_pk_bf16_f32 v168, v30, v22
	v_cvt_pk_bf16_f32 v169, v14, v6
	global_store_dwordx2 v[160:161], v[164:165], off
	global_store_dwordx2 v[160:161], v[168:169], off offset:256
	v_lshl_add_u64 v[160:161], v[160:161], 0, s[50:51]
	v_cndmask_b32_e64 v154, v79, v95, s[34:35]
	v_cndmask_b32_e64 v155, v71, v87, s[34:35]
	v_cndmask_b32_e64 v156, v15, v31, s[34:35]
	v_cndmask_b32_e64 v157, v7, v23, s[34:35]
	v_mov_b32_dpp v154, v154 quad_perm:[2,3,0,1] row_mask:0xf bank_mask:0xf
	v_mov_b32_dpp v155, v155 quad_perm:[2,3,0,1] row_mask:0xf bank_mask:0xf
	v_mov_b32_dpp v156, v156 quad_perm:[2,3,0,1] row_mask:0xf bank_mask:0xf
	v_mov_b32_dpp v157, v157 quad_perm:[2,3,0,1] row_mask:0xf bank_mask:0xf
	v_cndmask_b32_e64 v95, v95, v154, s[34:35]
	v_cndmask_b32_e64 v79, v154, v79, s[34:35]
	v_cndmask_b32_e64 v87, v87, v155, s[34:35]
	v_cndmask_b32_e64 v71, v155, v71, s[34:35]
	v_cndmask_b32_e64 v31, v31, v156, s[34:35]
	v_cndmask_b32_e64 v15, v156, v15, s[34:35]
	v_cndmask_b32_e64 v23, v23, v157, s[34:35]
	v_cndmask_b32_e64 v7, v157, v7, s[34:35]
	v_cndmask_b32_e64 v154, v87, v95, s[40:41]
	v_cndmask_b32_e64 v155, v71, v79, s[40:41]
	v_cndmask_b32_e64 v156, v23, v31, s[40:41]
	v_cndmask_b32_e64 v157, v7, v15, s[40:41]
	v_mov_b32_dpp v154, v154 quad_perm:[1,0,3,2] row_mask:0xf bank_mask:0xf
	v_mov_b32_dpp v155, v155 quad_perm:[1,0,3,2] row_mask:0xf bank_mask:0xf
	v_mov_b32_dpp v156, v156 quad_perm:[1,0,3,2] row_mask:0xf bank_mask:0xf
	v_mov_b32_dpp v157, v157 quad_perm:[1,0,3,2] row_mask:0xf bank_mask:0xf
	v_cndmask_b32_e64 v95, v95, v154, s[40:41]
	v_cndmask_b32_e64 v87, v154, v87, s[40:41]
	v_cndmask_b32_e64 v79, v79, v155, s[40:41]
	v_cndmask_b32_e64 v71, v155, v71, s[40:41]
	v_cndmask_b32_e64 v31, v31, v156, s[40:41]
	v_cndmask_b32_e64 v23, v156, v23, s[40:41]
	v_cndmask_b32_e64 v15, v15, v157, s[40:41]
	v_cndmask_b32_e64 v7, v157, v7, s[40:41]
	v_cvt_pk_bf16_f32 v164, v95, v87
	v_cvt_pk_bf16_f32 v165, v79, v71
	v_cvt_pk_bf16_f32 v168, v31, v23
	v_cvt_pk_bf16_f32 v169, v15, v7
	global_store_dwordx2 v[160:161], v[164:165], off
	global_store_dwordx2 v[160:161], v[168:169], off offset:256
	v_lshl_add_u64 v[160:161], v[160:161], 0, s[50:51]
	v_cndmask_b32_e64 v154, v80, v96, s[34:35]
	v_cndmask_b32_e64 v155, v72, v88, s[34:35]
	v_cndmask_b32_e64 v156, v16, v32, s[34:35]
	v_cndmask_b32_e64 v157, v8, v24, s[34:35]
	v_mov_b32_dpp v154, v154 quad_perm:[2,3,0,1] row_mask:0xf bank_mask:0xf
	v_mov_b32_dpp v155, v155 quad_perm:[2,3,0,1] row_mask:0xf bank_mask:0xf
	v_mov_b32_dpp v156, v156 quad_perm:[2,3,0,1] row_mask:0xf bank_mask:0xf
	v_mov_b32_dpp v157, v157 quad_perm:[2,3,0,1] row_mask:0xf bank_mask:0xf
	v_cndmask_b32_e64 v96, v96, v154, s[34:35]
	v_cndmask_b32_e64 v80, v154, v80, s[34:35]
	v_cndmask_b32_e64 v88, v88, v155, s[34:35]
	v_cndmask_b32_e64 v72, v155, v72, s[34:35]
	v_cndmask_b32_e64 v32, v32, v156, s[34:35]
	v_cndmask_b32_e64 v16, v156, v16, s[34:35]
	v_cndmask_b32_e64 v24, v24, v157, s[34:35]
	v_cndmask_b32_e64 v8, v157, v8, s[34:35]
	v_cndmask_b32_e64 v154, v88, v96, s[40:41]
	v_cndmask_b32_e64 v155, v72, v80, s[40:41]
	v_cndmask_b32_e64 v156, v24, v32, s[40:41]
	v_cndmask_b32_e64 v157, v8, v16, s[40:41]
	v_mov_b32_dpp v154, v154 quad_perm:[1,0,3,2] row_mask:0xf bank_mask:0xf
	v_mov_b32_dpp v155, v155 quad_perm:[1,0,3,2] row_mask:0xf bank_mask:0xf
	v_mov_b32_dpp v156, v156 quad_perm:[1,0,3,2] row_mask:0xf bank_mask:0xf
	v_mov_b32_dpp v157, v157 quad_perm:[1,0,3,2] row_mask:0xf bank_mask:0xf
	v_cndmask_b32_e64 v96, v96, v154, s[40:41]
	v_cndmask_b32_e64 v88, v154, v88, s[40:41]
	v_cndmask_b32_e64 v80, v80, v155, s[40:41]
	v_cndmask_b32_e64 v72, v155, v72, s[40:41]
	v_cndmask_b32_e64 v32, v32, v156, s[40:41]
	v_cndmask_b32_e64 v24, v156, v24, s[40:41]
	v_cndmask_b32_e64 v16, v16, v157, s[40:41]
	v_cndmask_b32_e64 v8, v157, v8, s[40:41]
	v_cvt_pk_bf16_f32 v164, v96, v88
	v_cvt_pk_bf16_f32 v165, v80, v72
	v_cvt_pk_bf16_f32 v168, v32, v24
	v_cvt_pk_bf16_f32 v169, v16, v8
	global_store_dwordx2 v[160:161], v[164:165], off
	global_store_dwordx2 v[160:161], v[168:169], off offset:256
	v_lshl_add_u64 v[160:161], v[160:161], 0, s[50:51]
	v_cndmask_b32_e64 v154, v81, v97, s[34:35]
	v_cndmask_b32_e64 v155, v73, v89, s[34:35]
	v_cndmask_b32_e64 v156, v17, v33, s[34:35]
	v_cndmask_b32_e64 v157, v9, v25, s[34:35]
	v_mov_b32_dpp v154, v154 quad_perm:[2,3,0,1] row_mask:0xf bank_mask:0xf
; DI bf16_t f2bf(float x) { unsigned u = __float_as_uint(x); u += 0x7fffu + ((u >> 16) & 1u); return (bf16_t)(u >> 16); }
; template <int EPI>
; DI void gemm8_epilogue(const GemmArgs& g, f32x4 (&acc)[2][2][4][2], const int brow, const int bcol, const int wr, const int wc, const int fr, const int fq) {
;     ...
;         if (bcol >= 2048) {
;           bf16_t* VT = (bf16_t*)g.out1;
; #pragma unroll
;           for (int m = 0; m < 4; ++m) {
;             const int row = r0 + m * 16, b = row >> 12, t = row & 4095;
; #pragma unroll
;             for (int n = 0; n < 2; ++n)
; #pragma unroll
;               for (int j = 0; j < 4; ++j) {
;                 const int c = cb - 2048 + n * 16 + fq * 4 + j;
;                 VT[((size_t)((b * 16 + (c >> 6)) * 64 + (c & 63))) * SEQ + t] = f2bf(acc[ai][bj][m][n][j]);
;               }
;           }
	v_mov_b32_dpp v155, v155 quad_perm:[2,3,0,1] row_mask:0xf bank_mask:0xf
	v_mov_b32_dpp v156, v156 quad_perm:[2,3,0,1] row_mask:0xf bank_mask:0xf
	v_mov_b32_dpp v157, v157 quad_perm:[2,3,0,1] row_mask:0xf bank_mask:0xf
	v_cndmask_b32_e64 v97, v97, v154, s[34:35]
	v_cndmask_b32_e64 v81, v154, v81, s[34:35]
	v_cndmask_b32_e64 v89, v89, v155, s[34:35]
	v_cndmask_b32_e64 v73, v155, v73, s[34:35]
	v_cndmask_b32_e64 v33, v33, v156, s[34:35]
	v_cndmask_b32_e64 v17, v156, v17, s[34:35]
	v_cndmask_b32_e64 v25, v25, v157, s[34:35]
	v_cndmask_b32_e64 v9, v157, v9, s[34:35]
	v_cndmask_b32_e64 v154, v89, v97, s[40:41]
	v_cndmask_b32_e64 v155, v73, v81, s[40:41]
	v_cndmask_b32_e64 v156, v25, v33, s[40:41]
	v_cndmask_b32_e64 v157, v9, v17, s[40:41]
	v_mov_b32_dpp v154, v154 quad_perm:[1,0,3,2] row_mask:0xf bank_mask:0xf
	v_mov_b32_dpp v155, v155 quad_perm:[1,0,3,2] row_mask:0xf bank_mask:0xf
	v_mov_b32_dpp v156, v156 quad_perm:[1,0,3,2] row_mask:0xf bank_mask:0xf
	v_mov_b32_dpp v157, v157 quad_perm:[1,0,3,2] row_mask:0xf bank_mask:0xf
	v_cndmask_b32_e64 v97, v97, v154, s[40:41]
	v_cndmask_b32_e64 v89, v154, v89, s[40:41]
	v_cndmask_b32_e64 v81, v81, v155, s[40:41]
	v_cndmask_b32_e64 v73, v155, v73, s[40:41]
	v_cndmask_b32_e64 v33, v33, v156, s[40:41]
	v_cndmask_b32_e64 v25, v156, v25, s[40:41]
	v_cndmask_b32_e64 v17, v17, v157, s[40:41]
	v_cndmask_b32_e64 v9, v157, v9, s[40:41]
	v_cvt_pk_bf16_f32 v164, v97, v89
	v_cvt_pk_bf16_f32 v165, v81, v73
	v_cvt_pk_bf16_f32 v168, v33, v25
	v_cvt_pk_bf16_f32 v169, v17, v9
	global_store_dwordx2 v[160:161], v[164:165], off
	global_store_dwordx2 v[160:161], v[168:169], off offset:256
	v_lshl_add_u64 v[160:161], v[160:161], 0, s[22:23]
	v_cndmask_b32_e64 v154, v74, v90, s[34:35]
	v_cndmask_b32_e64 v155, v66, v82, s[34:35]
	v_cndmask_b32_e64 v156, v10, v26, s[34:35]
	v_cndmask_b32_e64 v157, v2, v18, s[34:35]
	v_mov_b32_dpp v154, v154 quad_perm:[2,3,0,1] row_mask:0xf bank_mask:0xf
	v_mov_b32_dpp v155, v155 quad_perm:[2,3,0,1] row_mask:0xf bank_mask:0xf
	v_mov_b32_dpp v156, v156 quad_perm:[2,3,0,1] row_mask:0xf bank_mask:0xf
	v_mov_b32_dpp v157, v157 quad_perm:[2,3,0,1] row_mask:0xf bank_mask:0xf
	v_cndmask_b32_e64 v90, v90, v154, s[34:35]
	v_cndmask_b32_e64 v74, v154, v74, s[34:35]
	v_cndmask_b32_e64 v82, v82, v155, s[34:35]
	v_cndmask_b32_e64 v66, v155, v66, s[34:35]
	v_cndmask_b32_e64 v26, v26, v156, s[34:35]
	v_cndmask_b32_e64 v10, v156, v10, s[34:35]
	v_cndmask_b32_e64 v18, v18, v157, s[34:35]
	v_cndmask_b32_e64 v2, v157, v2, s[34:35]
	v_cndmask_b32_e64 v154, v82, v90, s[40:41]
	v_cndmask_b32_e64 v155, v66, v74, s[40:41]
	v_cndmask_b32_e64 v156, v18, v26, s[40:41]
	v_cndmask_b32_e64 v157, v2, v10, s[40:41]
	v_mov_b32_dpp v154, v154 quad_perm:[1,0,3,2] row_mask:0xf bank_mask:0xf
	v_mov_b32_dpp v155, v155 quad_perm:[1,0,3,2] row_mask:0xf bank_mask:0xf
	v_mov_b32_dpp v156, v156 quad_perm:[1,0,3,2] row_mask:0xf bank_mask:0xf
	v_mov_b32_dpp v157, v157 quad_perm:[1,0,3,2] row_mask:0xf bank_mask:0xf
	v_cndmask_b32_e64 v90, v90, v154, s[40:41]
	v_cndmask_b32_e64 v82, v154, v82, s[40:41]
	v_cndmask_b32_e64 v74, v74, v155, s[40:41]
	v_cndmask_b32_e64 v66, v155, v66, s[40:41]
	v_cndmask_b32_e64 v26, v26, v156, s[40:41]
	v_cndmask_b32_e64 v18, v156, v18, s[40:41]
	v_cndmask_b32_e64 v10, v10, v157, s[40:41]
	v_cndmask_b32_e64 v2, v157, v2, s[40:41]
	v_cvt_pk_bf16_f32 v164, v90, v82
	v_cvt_pk_bf16_f32 v165, v74, v66
	v_cvt_pk_bf16_f32 v168, v26, v18
	v_cvt_pk_bf16_f32 v169, v10, v2
	global_store_dwordx2 v[160:161], v[164:165], off
	global_store_dwordx2 v[160:161], v[168:169], off offset:256
	v_lshl_add_u64 v[160:161], v[160:161], 0, s[50:51]
	v_cndmask_b32_e64 v154, v75, v91, s[34:35]
	v_cndmask_b32_e64 v155, v67, v83, s[34:35]
	v_cndmask_b32_e64 v156, v11, v27, s[34:35]
	v_cndmask_b32_e64 v157, v3, v19, s[34:35]
	v_mov_b32_dpp v154, v154 quad_perm:[2,3,0,1] row_mask:0xf bank_mask:0xf
	v_mov_b32_dpp v155, v155 quad_perm:[2,3,0,1] row_mask:0xf bank_mask:0xf
	v_mov_b32_dpp v156, v156 quad_perm:[2,3,0,1] row_mask:0xf bank_mask:0xf
	v_mov_b32_dpp v157, v157 quad_perm:[2,3,0,1] row_mask:0xf bank_mask:0xf
	v_cndmask_b32_e64 v91, v91, v154, s[34:35]
	v_cndmask_b32_e64 v75, v154, v75, s[34:35]
	v_cndmask_b32_e64 v83, v83, v155, s[34:35]
	v_cndmask_b32_e64 v67, v155, v67, s[34:35]
	v_cndmask_b32_e64 v27, v27, v156, s[34:35]
	v_cndmask_b32_e64 v11, v156, v11, s[34:35]
	v_cndmask_b32_e64 v19, v19, v157, s[34:35]
	v_cndmask_b32_e64 v3, v157, v3, s[34:35]
	v_cndmask_b32_e64 v154, v83, v91, s[40:41]
	v_cndmask_b32_e64 v155, v67, v75, s[40:41]
	v_cndmask_b32_e64 v156, v19, v27, s[40:41]
	v_cndmask_b32_e64 v157, v3, v11, s[40:41]
	v_mov_b32_dpp v154, v154 quad_perm:[1,0,3,2] row_mask:0xf bank_mask:0xf
	v_mov_b32_dpp v155, v155 quad_perm:[1,0,3,2] row_mask:0xf bank_mask:0xf
	v_mov_b32_dpp v156, v156 quad_perm:[1,0,3,2] row_mask:0xf bank_mask:0xf
	v_mov_b32_dpp v157, v157 quad_perm:[1,0,3,2] row_mask:0xf bank_mask:0xf
	v_cndmask_b32_e64 v91, v91, v154, s[40:41]
	v_cndmask_b32_e64 v83, v154, v83, s[40:41]
	v_cndmask_b32_e64 v75, v75, v155, s[40:41]
	v_cndmask_b32_e64 v67, v155, v67, s[40:41]
	v_cndmask_b32_e64 v27, v27, v156, s[40:41]
	v_cndmask_b32_e64 v19, v156, v19, s[40:41]
	v_cndmask_b32_e64 v11, v11, v157, s[40:41]
	v_cndmask_b32_e64 v3, v157, v3, s[40:41]
	v_cvt_pk_bf16_f32 v164, v91, v83
	v_cvt_pk_bf16_f32 v165, v75, v67
	v_cvt_pk_bf16_f32 v168, v27, v19
	v_cvt_pk_bf16_f32 v169, v11, v3
	global_store_dwordx2 v[160:161], v[164:165], off
	global_store_dwordx2 v[160:161], v[168:169], off offset:256
	v_lshl_add_u64 v[160:161], v[160:161], 0, s[50:51]
	v_cndmask_b32_e64 v154, v76, v92, s[34:35]
	v_cndmask_b32_e64 v155, v68, v84, s[34:35]
; DI bf16_t f2bf(float x) { unsigned u = __float_as_uint(x); u += 0x7fffu + ((u >> 16) & 1u); return (bf16_t)(u >> 16); }
; template <int EPI>
; DI void gemm8_epilogue(const GemmArgs& g, f32x4 (&acc)[2][2][4][2], const int brow, const int bcol, const int wr, const int wc, const int fr, const int fq) {
;     ...
;         if (bcol >= 2048) {
;           bf16_t* VT = (bf16_t*)g.out1;
; #pragma unroll
;           for (int m = 0; m < 4; ++m) {
;             const int row = r0 + m * 16, b = row >> 12, t = row & 4095;
; #pragma unroll
;             for (int n = 0; n < 2; ++n)
; #pragma unroll
;               for (int j = 0; j < 4; ++j) {
;                 const int c = cb - 2048 + n * 16 + fq * 4 + j;
;                 VT[((size_t)((b * 16 + (c >> 6)) * 64 + (c & 63))) * SEQ + t] = f2bf(acc[ai][bj][m][n][j]);
;               }
;           }
	v_cndmask_b32_e64 v156, v12, v28, s[34:35]
	v_cndmask_b32_e64 v157, v4, v20, s[34:35]
	v_mov_b32_dpp v154, v154 quad_perm:[2,3,0,1] row_mask:0xf bank_mask:0xf
	v_mov_b32_dpp v155, v155 quad_perm:[2,3,0,1] row_mask:0xf bank_mask:0xf
	v_mov_b32_dpp v156, v156 quad_perm:[2,3,0,1] row_mask:0xf bank_mask:0xf
	v_mov_b32_dpp v157, v157 quad_perm:[2,3,0,1] row_mask:0xf bank_mask:0xf
	v_cndmask_b32_e64 v92, v92, v154, s[34:35]
	v_cndmask_b32_e64 v76, v154, v76, s[34:35]
	v_cndmask_b32_e64 v84, v84, v155, s[34:35]
	v_cndmask_b32_e64 v68, v155, v68, s[34:35]
	v_cndmask_b32_e64 v28, v28, v156, s[34:35]
	v_cndmask_b32_e64 v12, v156, v12, s[34:35]
	v_cndmask_b32_e64 v20, v20, v157, s[34:35]
	v_cndmask_b32_e64 v4, v157, v4, s[34:35]
	v_cndmask_b32_e64 v154, v84, v92, s[40:41]
	v_cndmask_b32_e64 v155, v68, v76, s[40:41]
	v_cndmask_b32_e64 v156, v20, v28, s[40:41]
	v_cndmask_b32_e64 v157, v4, v12, s[40:41]
	v_mov_b32_dpp v154, v154 quad_perm:[1,0,3,2] row_mask:0xf bank_mask:0xf
	v_mov_b32_dpp v155, v155 quad_perm:[1,0,3,2] row_mask:0xf bank_mask:0xf
	v_mov_b32_dpp v156, v156 quad_perm:[1,0,3,2] row_mask:0xf bank_mask:0xf
	v_mov_b32_dpp v157, v157 quad_perm:[1,0,3,2] row_mask:0xf bank_mask:0xf
	v_cndmask_b32_e64 v92, v92, v154, s[40:41]
	v_cndmask_b32_e64 v84, v154, v84, s[40:41]
	v_cndmask_b32_e64 v76, v76, v155, s[40:41]
	v_cndmask_b32_e64 v68, v155, v68, s[40:41]
	v_cndmask_b32_e64 v28, v28, v156, s[40:41]
	v_cndmask_b32_e64 v20, v156, v20, s[40:41]
	v_cndmask_b32_e64 v12, v12, v157, s[40:41]
	v_cndmask_b32_e64 v4, v157, v4, s[40:41]
	v_cvt_pk_bf16_f32 v164, v92, v84
	v_cvt_pk_bf16_f32 v165, v76, v68
	v_cvt_pk_bf16_f32 v168, v28, v20
	v_cvt_pk_bf16_f32 v169, v12, v4
	global_store_dwordx2 v[160:161], v[164:165], off
	global_store_dwordx2 v[160:161], v[168:169], off offset:256
	v_lshl_add_u64 v[160:161], v[160:161], 0, s[50:51]
	v_cndmask_b32_e64 v154, v77, v93, s[34:35]
	v_cndmask_b32_e64 v155, v69, v85, s[34:35]
	v_cndmask_b32_e64 v156, v13, v29, s[34:35]
	v_cndmask_b32_e64 v157, v5, v21, s[34:35]
	v_mov_b32_dpp v154, v154 quad_perm:[2,3,0,1] row_mask:0xf bank_mask:0xf
	v_mov_b32_dpp v155, v155 quad_perm:[2,3,0,1] row_mask:0xf bank_mask:0xf
	v_mov_b32_dpp v156, v156 quad_perm:[2,3,0,1] row_mask:0xf bank_mask:0xf
	v_mov_b32_dpp v157, v157 quad_perm:[2,3,0,1] row_mask:0xf bank_mask:0xf
	v_cndmask_b32_e64 v93, v93, v154, s[34:35]
	v_cndmask_b32_e64 v77, v154, v77, s[34:35]
	v_cndmask_b32_e64 v85, v85, v155, s[34:35]
	v_cndmask_b32_e64 v69, v155, v69, s[34:35]
	v_cndmask_b32_e64 v29, v29, v156, s[34:35]
	v_cndmask_b32_e64 v13, v156, v13, s[34:35]
	v_cndmask_b32_e64 v21, v21, v157, s[34:35]
	v_cndmask_b32_e64 v5, v157, v5, s[34:35]
	v_cndmask_b32_e64 v154, v85, v93, s[40:41]
	v_cndmask_b32_e64 v155, v69, v77, s[40:41]
	v_cndmask_b32_e64 v156, v21, v29, s[40:41]
	v_cndmask_b32_e64 v157, v5, v13, s[40:41]
	v_mov_b32_dpp v154, v154 quad_perm:[1,0,3,2] row_mask:0xf bank_mask:0xf
	v_mov_b32_dpp v155, v155 quad_perm:[1,0,3,2] row_mask:0xf bank_mask:0xf
	v_mov_b32_dpp v156, v156 quad_perm:[1,0,3,2] row_mask:0xf bank_mask:0xf
	v_mov_b32_dpp v157, v157 quad_perm:[1,0,3,2] row_mask:0xf bank_mask:0xf
	v_cndmask_b32_e64 v93, v93, v154, s[40:41]
	v_cndmask_b32_e64 v85, v154, v85, s[40:41]
	v_cndmask_b32_e64 v77, v77, v155, s[40:41]
	v_cndmask_b32_e64 v69, v155, v69, s[40:41]
	v_cndmask_b32_e64 v29, v29, v156, s[40:41]
	v_cndmask_b32_e64 v21, v156, v21, s[40:41]
	v_cndmask_b32_e64 v13, v13, v157, s[40:41]
	v_cndmask_b32_e64 v5, v157, v5, s[40:41]
	v_cvt_pk_bf16_f32 v164, v93, v85
	v_cvt_pk_bf16_f32 v165, v77, v69
	v_cvt_pk_bf16_f32 v168, v29, v21
	v_cvt_pk_bf16_f32 v169, v13, v5
	global_store_dwordx2 v[160:161], v[164:165], off
	global_store_dwordx2 v[160:161], v[168:169], off offset:256
	s_branch .LBB0_400
	v_and_b32_e32 v0, 0xfcf, v140
	s_andn2_b64 vcc, exec, s[40:41]
	v_lshlrev_b32_e32 v0, 1, v0
	s_cbranch_vccnz .LBB0_388
; DI bf16_t f2bf(float x) { unsigned u = __float_as_uint(x); u += 0x7fffu + ((u >> 16) & 1u); return (bf16_t)(u >> 16); }
; template <int EPI>
; DI void gemm8_epilogue(const GemmArgs& g, f32x4 (&acc)[2][2][4][2], const int brow, const int bcol, const int wr, const int wc, const int fr, const int fq) {
;     ...
;         if (bcol >= 2048) {
;           bf16_t* VT = (bf16_t*)g.out1;
; #pragma unroll
;           for (int m = 0; m < 4; ++m) {
;             const int row = r0 + m * 16, b = row >> 12, t = row & 4095;
; #pragma unroll
;             for (int n = 0; n < 2; ++n)
; #pragma unroll
;               for (int j = 0; j < 4; ++j) {
;                 const int c = cb - 2048 + n * 16 + fq * 4 + j;
;                 VT[((size_t)((b * 16 + (c >> 6)) * 64 + (c & 63))) * SEQ + t] = f2bf(acc[ai][bj][m][n][j]);
;               }
;           }
	s_ashr_i32 s22, s24, 2
	s_and_b32 s22, s22, 0xfffffc00
	s_add_i32 s22, s22, s23
	v_add_u32_e32 v154, s22, v152
	v_ashrrev_i32_e32 v155, 31, v154
	v_lshl_add_u64 v[156:157], s[82:83], 0, v[0:1]
	v_bfe_u32 v153, v126, 16, 1
	v_lshlrev_b64 v[158:159], 13, v[154:155]
	v_add3_u32 v126, v126, v153, s93
	v_lshl_add_u64 v[158:159], v[156:157], 0, v[158:159]
	global_store_short_d16_hi v[158:159], v126, off
	v_bfe_u32 v126, v127, 16, 1
	v_add3_u32 v153, v127, v126, s93
	v_or_b32_e32 v126, 1, v154
	v_ashrrev_i32_e32 v127, 31, v126
	v_lshlrev_b64 v[126:127], 13, v[126:127]
	v_or_b32_e32 v160, 2, v154
	v_lshl_add_u64 v[126:127], v[156:157], 0, v[126:127]
	v_ashrrev_i32_e32 v161, 31, v160
	global_store_short_d16_hi v[126:127], v153, off
	v_bfe_u32 v153, v128, 16, 1
	v_lshlrev_b64 v[160:161], 13, v[160:161]
	v_add3_u32 v128, v128, v153, s93
	v_lshl_add_u64 v[160:161], v[156:157], 0, v[160:161]
	global_store_short_d16_hi v[160:161], v128, off
	v_bfe_u32 v128, v129, 16, 1
	v_add3_u32 v153, v129, v128, s93
	v_or_b32_e32 v128, 3, v154
	v_ashrrev_i32_e32 v129, 31, v128
	v_lshlrev_b64 v[128:129], 13, v[128:129]
	v_or_b32_e32 v164, 16, v154
	v_lshl_add_u64 v[128:129], v[156:157], 0, v[128:129]
	v_ashrrev_i32_e32 v165, 31, v164
	global_store_short_d16_hi v[128:129], v153, off
	v_bfe_u32 v153, v122, 16, 1
	v_lshlrev_b64 v[164:165], 13, v[164:165]
	v_add3_u32 v122, v122, v153, s93
	v_lshl_add_u64 v[164:165], v[156:157], 0, v[164:165]
	global_store_short_d16_hi v[164:165], v122, off
	v_bfe_u32 v122, v123, 16, 1
	v_add3_u32 v153, v123, v122, s93
	v_or_b32_e32 v122, 17, v154
	v_ashrrev_i32_e32 v123, 31, v122
	v_lshlrev_b64 v[122:123], 13, v[122:123]
	v_or_b32_e32 v168, 18, v154
	v_lshl_add_u64 v[122:123], v[156:157], 0, v[122:123]
	v_ashrrev_i32_e32 v169, 31, v168
	global_store_short_d16_hi v[122:123], v153, off
	v_bfe_u32 v153, v124, 16, 1
	v_lshlrev_b64 v[168:169], 13, v[168:169]
	v_add3_u32 v124, v124, v153, s93
	v_lshl_add_u64 v[168:169], v[156:157], 0, v[168:169]
	global_store_short_d16_hi v[168:169], v124, off
	v_bfe_u32 v124, v125, 16, 1
	v_add3_u32 v153, v125, v124, s93
	v_or_b32_e32 v124, 19, v154
	v_ashrrev_i32_e32 v125, 31, v124
	v_lshlrev_b64 v[124:125], 13, v[124:125]
	v_lshl_add_u64 v[124:125], v[156:157], 0, v[124:125]
	global_store_short_d16_hi v[124:125], v153, off
	v_bfe_u32 v153, v118, 16, 1
	v_add3_u32 v118, v118, v153, s93
	global_store_short_d16_hi v[158:159], v118, off offset:32
	v_bfe_u32 v118, v119, 16, 1
	v_add3_u32 v118, v119, v118, s93
	global_store_short_d16_hi v[126:127], v118, off offset:32
	v_bfe_u32 v118, v120, 16, 1
	v_add3_u32 v118, v120, v118, s93
	global_store_short_d16_hi v[160:161], v118, off offset:32
	v_bfe_u32 v118, v121, 16, 1
	v_add3_u32 v118, v121, v118, s93
	global_store_short_d16_hi v[128:129], v118, off offset:32
	v_bfe_u32 v118, v114, 16, 1
	v_add3_u32 v114, v114, v118, s93
	global_store_short_d16_hi v[164:165], v114, off offset:32
	v_bfe_u32 v114, v115, 16, 1
	v_add3_u32 v114, v115, v114, s93
	global_store_short_d16_hi v[122:123], v114, off offset:32
	v_bfe_u32 v114, v116, 16, 1
	v_add3_u32 v114, v116, v114, s93
	global_store_short_d16_hi v[168:169], v114, off offset:32
	v_bfe_u32 v114, v117, 16, 1
	v_add3_u32 v114, v117, v114, s93
	global_store_short_d16_hi v[124:125], v114, off offset:32
	v_bfe_u32 v114, v110, 16, 1
	v_add3_u32 v110, v110, v114, s93
	global_store_short_d16_hi v[158:159], v110, off offset:64
	v_bfe_u32 v110, v111, 16, 1
	v_add3_u32 v110, v111, v110, s93
	global_store_short_d16_hi v[126:127], v110, off offset:64
	v_bfe_u32 v110, v112, 16, 1
	v_add3_u32 v110, v112, v110, s93
	global_store_short_d16_hi v[160:161], v110, off offset:64
	v_bfe_u32 v110, v113, 16, 1
	v_add3_u32 v110, v113, v110, s93
	global_store_short_d16_hi v[128:129], v110, off offset:64
	v_bfe_u32 v110, v106, 16, 1
	v_add3_u32 v106, v106, v110, s93
	global_store_short_d16_hi v[164:165], v106, off offset:64
	v_bfe_u32 v106, v107, 16, 1
	v_add3_u32 v106, v107, v106, s93
	global_store_short_d16_hi v[122:123], v106, off offset:64
	v_bfe_u32 v106, v108, 16, 1
	v_add3_u32 v106, v108, v106, s93
	global_store_short_d16_hi v[168:169], v106, off offset:64
	v_bfe_u32 v106, v109, 16, 1
	v_add3_u32 v106, v109, v106, s93
	global_store_short_d16_hi v[124:125], v106, off offset:64
	v_bfe_u32 v106, v102, 16, 1
	v_add3_u32 v102, v102, v106, s93
	global_store_short_d16_hi v[158:159], v102, off offset:96
	v_bfe_u32 v102, v103, 16, 1
	v_add3_u32 v102, v103, v102, s93
	global_store_short_d16_hi v[126:127], v102, off offset:96
	v_bfe_u32 v102, v104, 16, 1
	v_add3_u32 v102, v104, v102, s93
	global_store_short_d16_hi v[160:161], v102, off offset:96
	v_bfe_u32 v102, v105, 16, 1
	v_add3_u32 v102, v105, v102, s93
	global_store_short_d16_hi v[128:129], v102, off offset:96
	v_bfe_u32 v102, v98, 16, 1
	v_add3_u32 v98, v98, v102, s93
	global_store_short_d16_hi v[164:165], v98, off offset:96
	v_bfe_u32 v98, v99, 16, 1
	v_add3_u32 v98, v99, v98, s93
	global_store_short_d16_hi v[122:123], v98, off offset:96
	v_bfe_u32 v98, v100, 16, 1
	v_add3_u32 v98, v100, v98, s93
	global_store_short_d16_hi v[168:169], v98, off offset:96
	v_bfe_u32 v98, v101, 16, 1
	v_add3_u32 v98, v101, v98, s93
	global_store_short_d16_hi v[124:125], v98, off offset:96

; DI unsigned pack2(float a, float b) { f32x2 v = {a, b}; return __builtin_bit_cast(unsigned, __builtin_convertvector(v, hwbf16x2)); }
; DI int otid() { int t = threadIdx.x; asm volatile("" : "+v"(t)); return t; }
; DI void rownorm_phase(const float* __restrict__ src, bf16_t* __restrict__ dst) {
;   const int lane = otid() & 63, gw = blockIdx.x * 8 + (otid() >> 6), nw = gridDim.x * 8;
;   for (int row = gw; row < NT; row += nw) {
;     const f32x4* xr = (const f32x4*)(src + (size_t)row * DM) + lane;
;     f32x4 v[4]; float s = 0.f;
; #pragma unroll
;     for (int j = 0; j < 4; ++j) { v[j] = xr[64 * j]; s += v[j].x * v[j].x + v[j].y * v[j].y + v[j].z * v[j].z + v[j].w * v[j].w; }
;     s = wave_sum(s);
;     const float rstd = rsqrtf(s * (1.f / DM) + 1e-6f);
;     u32x2* o = (u32x2*)(dst + (size_t)row * DM) + lane;
; #pragma unroll
;     for (int j = 0; j < 4; ++j) { u32x2 w; w.x = pack2(v[j].x * rstd, v[j].y * rstd); w.y = pack2(v[j].z * rstd, v[j].w * rstd); o[64 * j] = w; }
;   }
; }
.LBB0_1129:
	s_andn2_b64 vcc, exec, s[0:1]
	s_cbranch_vccnz .LBB0_278
	s_cmp_eq_u32 s4, 11
	s_mov_b64 s[0:1], -1
	s_mov_b32 s2, 0x800000
	s_cbranch_scc1 .LBB0_1136
	v_mov_b32_e32 v0, v167
	v_mov_b32_e32 v2, v167
	s_mov_b32 s0, 0x8000
	v_ashrrev_i32_e32 v2, 6, v2
	v_add_u32_e32 v2, s54, v2
	v_cmp_gt_i32_e32 vcc, s0, v2
	s_and_saveexec_b64 s[0:1], vcc
	s_cbranch_execz .LBB0_1134
	s_waitcnt vmcnt(0) lgkmcnt(0)
	v_readfirstlane_b32 s2, v2
	v_readlane_b32 s8, v254, 47
	v_readlane_b32 s9, v254, 48
	v_readlane_b32 s34, v254, 45
	v_readlane_b32 s35, v254, 46
	v_and_b32_e32 v0, 63, v167
	v_lshlrev_b32_e32 v3, 4, v0
	v_lshlrev_b32_e32 v0, 5, v0
	s_mov_b32 vcc_lo, s2
	s_mov_b32 vcc_hi, s2
	s_lshl_b32 s2, s2, 12
	s_add_u32 s8, s8, s2
	s_addc_u32 s9, s9, 0
	s_lshr_b32 s2, s2, 1
	s_add_u32 s34, s34, s2
	s_addc_u32 s35, s35, 0
	global_load_dwordx4 v[4:7], v0, s[8:9] offset:-3072
	global_load_dwordx4 v[8:11], v0, s[8:9] offset:-3056
	global_load_dwordx4 v[12:15], v0, s[8:9] offset:-1024
	global_load_dwordx4 v[16:19], v0, s[8:9] offset:-1008
	s_add_i32 vcc_hi, vcc_hi, s88
	s_lshl_b32 s2, s88, 12
	s_cmp_lt_i32 vcc_hi, 0x8000
	s_cselect_b32 s2, s2, 0
	s_add_u32 s8, s8, s2
	s_addc_u32 s9, s9, 0
	global_load_dwordx4 v[20:23], v0, s[8:9] offset:-3072
	global_load_dwordx4 v[24:27], v0, s[8:9] offset:-3056
	global_load_dwordx4 v[28:31], v0, s[8:9] offset:-1024
	global_load_dwordx4 v[32:35], v0, s[8:9] offset:-1008
	s_waitcnt vmcnt(4)
	s_branch .Lrn_compute_a
.Lrn_loop:
	s_waitcnt vmcnt(6)
.Lrn_compute_a:
	v_mul_f32_e32 v2, v4, v4
	v_fmac_f32_e32 v2, v5, v5
	v_fmac_f32_e32 v2, v6, v6
	v_fmac_f32_e32 v2, v7, v7
	v_fmac_f32_e32 v2, v8, v8
	v_fmac_f32_e32 v2, v9, v9
	v_fmac_f32_e32 v2, v10, v10
	v_fmac_f32_e32 v2, v11, v11
	v_fmac_f32_e32 v2, v12, v12
	v_fmac_f32_e32 v2, v13, v13
	v_fmac_f32_e32 v2, v14, v14
	v_fmac_f32_e32 v2, v15, v15
	v_fmac_f32_e32 v2, v16, v16
	v_fmac_f32_e32 v2, v17, v17
	v_fmac_f32_e32 v2, v18, v18
	v_fmac_f32_e32 v2, v19, v19
	s_nop 1
	v_add_f32_dpp v2, v2, v2 quad_perm:[1,0,3,2] row_mask:0xf bank_mask:0xf
	s_nop 1
	v_add_f32_dpp v2, v2, v2 quad_perm:[2,3,0,1] row_mask:0xf bank_mask:0xf
	s_nop 1
	v_add_f32_dpp v2, v2, v2 row_ror:4 row_mask:0xf bank_mask:0xf
	s_nop 1
	v_add_f32_dpp v2, v2, v2 row_ror:8 row_mask:0xf bank_mask:0xf
	s_nop 1
	v_add_f32_dpp v2, v2, v2 row_bcast:15 row_mask:0xa bank_mask:0xf
	s_nop 1
	v_add_f32_dpp v2, v2, v2 row_bcast:31 row_mask:0xc bank_mask:0xf
	s_nop 1
	v_readlane_b32 s2, v2, 63
	s_nop 3
	v_mov_b32_e32 v2, s2
	v_fmamk_f32 v2, v2, 0x3a800000, v177
	v_rsq_f32_e32 v2, v2
	s_nop 1
	v_pk_mul_f32 v[4:5], v[4:5], v[2:3] op_sel_hi:[1,0]
	v_pk_mul_f32 v[6:7], v[6:7], v[2:3] op_sel_hi:[1,0]
	v_pk_mul_f32 v[8:9], v[8:9], v[2:3] op_sel_hi:[1,0]
	v_pk_mul_f32 v[10:11], v[10:11], v[2:3] op_sel_hi:[1,0]
	v_pk_mul_f32 v[12:13], v[12:13], v[2:3] op_sel_hi:[1,0]
	v_pk_mul_f32 v[14:15], v[14:15], v[2:3] op_sel_hi:[1,0]
	v_pk_mul_f32 v[16:17], v[16:17], v[2:3] op_sel_hi:[1,0]
	v_pk_mul_f32 v[18:19], v[18:19], v[2:3] op_sel_hi:[1,0]
	v_cvt_pk_bf16_f32 v4, v4, v5
	v_cvt_pk_bf16_f32 v5, v6, v7
	v_cvt_pk_bf16_f32 v6, v8, v9
	v_cvt_pk_bf16_f32 v7, v10, v11
	v_cvt_pk_bf16_f32 v12, v12, v13
	v_cvt_pk_bf16_f32 v13, v14, v15
	v_cvt_pk_bf16_f32 v14, v16, v17
	v_cvt_pk_bf16_f32 v15, v18, v19
	global_store_dwordx4 v3, v[4:7], s[34:35] offset:-1024
	global_store_dwordx4 v3, v[12:15], s[34:35]
	s_lshl_b32 s2, s88, 11
	s_add_u32 s34, s34, s2
	s_addc_u32 s35, s35, 0
	s_add_i32 vcc_lo, vcc_lo, s88
	s_cmp_lt_i32 vcc_lo, 0x8000
	s_cbranch_scc0 .Lrn_done
	s_add_i32 vcc_hi, vcc_hi, s88
	s_lshl_b32 s2, s88, 12
	s_cmp_lt_i32 vcc_hi, 0x8000
	s_cselect_b32 s2, s2, 0
	s_add_u32 s8, s8, s2
	s_addc_u32 s9, s9, 0
	global_load_dwordx4 v[4:7], v0, s[8:9] offset:-3072
	global_load_dwordx4 v[8:11], v0, s[8:9] offset:-3056
	global_load_dwordx4 v[12:15], v0, s[8:9] offset:-1024
	global_load_dwordx4 v[16:19], v0, s[8:9] offset:-1008
	s_waitcnt vmcnt(6)
	v_mul_f32_e32 v2, v20, v20
	v_fmac_f32_e32 v2, v21, v21
	v_fmac_f32_e32 v2, v22, v22
	v_fmac_f32_e32 v2, v23, v23
	v_fmac_f32_e32 v2, v24, v24
	v_fmac_f32_e32 v2, v25, v25
	v_fmac_f32_e32 v2, v26, v26
	v_fmac_f32_e32 v2, v27, v27
	v_fmac_f32_e32 v2, v28, v28
	v_fmac_f32_e32 v2, v29, v29
	v_fmac_f32_e32 v2, v30, v30
	v_fmac_f32_e32 v2, v31, v31
	v_fmac_f32_e32 v2, v32, v32
	v_fmac_f32_e32 v2, v33, v33
	v_fmac_f32_e32 v2, v34, v34
	v_fmac_f32_e32 v2, v35, v35
	s_nop 1
	v_add_f32_dpp v2, v2, v2 quad_perm:[1,0,3,2] row_mask:0xf bank_mask:0xf
	s_nop 1
	v_add_f32_dpp v2, v2, v2 quad_perm:[2,3,0,1] row_mask:0xf bank_mask:0xf
	s_nop 1
	v_add_f32_dpp v2, v2, v2 row_ror:4 row_mask:0xf bank_mask:0xf
	s_nop 1
	v_add_f32_dpp v2, v2, v2 row_ror:8 row_mask:0xf bank_mask:0xf
	s_nop 1
	v_add_f32_dpp v2, v2, v2 row_bcast:15 row_mask:0xa bank_mask:0xf
	s_nop 1
	v_add_f32_dpp v2, v2, v2 row_bcast:31 row_mask:0xc bank_mask:0xf
	s_nop 1
	v_readlane_b32 s2, v2, 63
	s_nop 3
	v_mov_b32_e32 v2, s2
	v_fmamk_f32 v2, v2, 0x3a800000, v177
	v_rsq_f32_e32 v2, v2
	s_nop 1
	v_pk_mul_f32 v[20:21], v[20:21], v[2:3] op_sel_hi:[1,0]
	v_pk_mul_f32 v[22:23], v[22:23], v[2:3] op_sel_hi:[1,0]
	v_pk_mul_f32 v[24:25], v[24:25], v[2:3] op_sel_hi:[1,0]
	v_pk_mul_f32 v[26:27], v[26:27], v[2:3] op_sel_hi:[1,0]
	v_pk_mul_f32 v[28:29], v[28:29], v[2:3] op_sel_hi:[1,0]
	v_pk_mul_f32 v[30:31], v[30:31], v[2:3] op_sel_hi:[1,0]
	v_pk_mul_f32 v[32:33], v[32:33], v[2:3] op_sel_hi:[1,0]
	v_pk_mul_f32 v[34:35], v[34:35], v[2:3] op_sel_hi:[1,0]
	v_cvt_pk_bf16_f32 v20, v20, v21
	v_cvt_pk_bf16_f32 v21, v22, v23
	v_cvt_pk_bf16_f32 v22, v24, v25
	v_cvt_pk_bf16_f32 v23, v26, v27
	v_cvt_pk_bf16_f32 v28, v28, v29
	v_cvt_pk_bf16_f32 v29, v30, v31
	v_cvt_pk_bf16_f32 v30, v32, v33
	v_cvt_pk_bf16_f32 v31, v34, v35
	global_store_dwordx4 v3, v[20:23], s[34:35] offset:-1024
	global_store_dwordx4 v3, v[28:31], s[34:35]
	s_lshl_b32 s2, s88, 11
	s_add_u32 s34, s34, s2
	s_addc_u32 s35, s35, 0
	s_add_i32 vcc_lo, vcc_lo, s88
	s_cmp_lt_i32 vcc_lo, 0x8000
	s_cbranch_scc0 .Lrn_done
	s_add_i32 vcc_hi, vcc_hi, s88
	s_lshl_b32 s2, s88, 12
	s_cmp_lt_i32 vcc_hi, 0x8000
	s_cselect_b32 s2, s2, 0
	s_add_u32 s8, s8, s2
	s_addc_u32 s9, s9, 0
	global_load_dwordx4 v[20:23], v0, s[8:9] offset:-3072
	global_load_dwordx4 v[24:27], v0, s[8:9] offset:-3056
	global_load_dwordx4 v[28:31], v0, s[8:9] offset:-1024
	global_load_dwordx4 v[32:35], v0, s[8:9] offset:-1008
	s_branch .Lrn_loop
